# non-temporal U loads in the pooling phase (on top of the previous streaming hints)
# speedup vs baseline: 1.0096x; 1.0096x over previous
; template <int WIN> __device__ __forceinline__ void pool_chunk(const bf16_t* Ub, bf16_t* Pb, int t0, int L) {
;     constexpr int LEFT = WIN / 2, RIGHT = WIN - 1 - LEFT, NR = 8 + WIN - 1;
;     u32x4 rw[NR];
; #pragma unroll
;     for (int k = 0; k < NR; ++k) { const int t = t0 - LEFT + k; rw[k] = (t >= 0 && t < L) ? *(const u32x4*)(Ub + (size_t)t * DM) : (u32x4){0u, 0u, 0u, 0u}; }
; __global__ void __launch_bounds__(NWAVES * 64, 2) mk_fwd(Args args) {
;     ...
;             const int cc = item & 255, row0 = (item >> 8) * 8;
;             int base, L; if (row0 < ML) { base = row0 & ~(SEQ - 1); L = SEQ; } else { base = ML + ((row0 - ML) & ~(CTXL - 1)); L = CTXL; }
;             const int t0 = row0 - base, gidx = cc >> 6;
;             const bf16_t* Ub = U + (size_t)base * DM + cc * 8; bf16_t* Pb = P + (size_t)base * DM + cc * 8;
;             switch (gidx) {
;                 case 0: pool_chunk<2>(Ub, Pb, t0, L); break;
;                 case 1: pool_chunk<4>(Ub, Pb, t0, L); break;
;                 case 2: pool_chunk<8>(Ub, Pb, t0, L); break;
;                 default: pool_chunk<16>(Ub, Pb, t0, L); break;
.LBB0_385:
	v_ashrrev_i32_e32 v0, 5, v130
	v_and_b32_e32 v1, -8, v0
	v_cmp_gt_i32_e32 vcc, s22, v1
	s_nop 1
	v_cndmask_b32_e32 v2, v134, v135, vcc
	v_and_b32_e32 v0, v2, v0
	v_sub_u32_e32 v100, v1, v0
	v_ashrrev_i32_e32 v1, 31, v0
	v_lshlrev_b64 v[0:1], 12, v[0:1]
	v_cndmask_b32_e32 v136, v132, v133, vcc
	v_lshl_add_u64 v[104:105], v[94:95], 0, v[0:1]
	v_lshl_add_u64 v[98:99], v[96:97], 0, v[0:1]
	v_cmp_lt_i32_e32 vcc, 1, v131
	s_and_saveexec_b64 s[10:11], vcc
	s_xor_b64 s[10:11], exec, s[10:11]
	s_cbranch_execz .LBB0_467
	v_cmp_lt_i32_e32 vcc, 2, v131
	s_and_saveexec_b64 s[18:19], vcc
	s_xor_b64 s[18:19], exec, s[18:19]
	s_cbranch_execz .LBB0_434
	v_add_u32_e32 v92, -8, v100
	v_cmp_lt_u32_e32 vcc, v92, v136
	v_mov_b32_e32 v8, 0
	v_mov_b32_e32 v12, 0
	v_mov_b32_e32 v13, 0
	v_mov_b32_e32 v14, 0
	v_mov_b32_e32 v15, 0
	s_and_saveexec_b64 s[20:21], vcc
	s_cbranch_execz .LBB0_389
	v_lshlrev_b64 v[0:1], 12, v[92:93]
	v_lshl_add_u64 v[0:1], v[104:105], 0, v[0:1]
	global_load_dwordx4 v[12:15], v[0:1], off nt
.LBB0_389:
	s_or_b64 exec, exec, s[20:21]
	v_add_u32_e32 v92, -7, v100
	v_cmp_lt_u32_e32 vcc, v92, v136
	v_mov_b32_e32 v9, 0
	v_mov_b32_e32 v10, 0
	v_mov_b32_e32 v11, 0
	s_and_saveexec_b64 s[20:21], vcc
	s_cbranch_execz .LBB0_391
	v_lshlrev_b64 v[0:1], 12, v[92:93]
	v_lshl_add_u64 v[0:1], v[104:105], 0, v[0:1]
	global_load_dwordx4 v[8:11], v[0:1], off nt
.LBB0_391:
	s_or_b64 exec, exec, s[20:21]
	v_add_u32_e32 v92, -6, v100
	v_cmp_lt_u32_e32 vcc, v92, v136
	v_mov_b32_e32 v16, 0
	v_mov_b32_e32 v24, 0
	v_mov_b32_e32 v25, 0
	v_mov_b32_e32 v26, 0
	v_mov_b32_e32 v27, 0
	s_and_saveexec_b64 s[20:21], vcc
	s_cbranch_execz .LBB0_393
	v_lshlrev_b64 v[0:1], 12, v[92:93]
	v_lshl_add_u64 v[0:1], v[104:105], 0, v[0:1]
	global_load_dwordx4 v[24:27], v[0:1], off nt
.LBB0_393:
	s_or_b64 exec, exec, s[20:21]
	v_add_u32_e32 v92, -5, v100
	v_cmp_lt_u32_e32 vcc, v92, v136
	v_mov_b32_e32 v17, 0
	v_mov_b32_e32 v18, 0
	v_mov_b32_e32 v19, 0
	s_and_saveexec_b64 s[20:21], vcc
	s_cbranch_execz .LBB0_395
	v_lshlrev_b64 v[0:1], 12, v[92:93]
	v_lshl_add_u64 v[0:1], v[104:105], 0, v[0:1]
	global_load_dwordx4 v[16:19], v[0:1], off nt
.LBB0_395:
	s_or_b64 exec, exec, s[20:21]
	v_add_u32_e32 v92, -4, v100
	v_cmp_lt_u32_e32 vcc, v92, v136
	v_mov_b32_e32 v32, 0
	v_mov_b32_e32 v36, 0
	v_mov_b32_e32 v37, 0
	v_mov_b32_e32 v38, 0
	v_mov_b32_e32 v39, 0
	s_and_saveexec_b64 s[20:21], vcc
	s_cbranch_execz .LBB0_397
	v_lshlrev_b64 v[0:1], 12, v[92:93]
	v_lshl_add_u64 v[0:1], v[104:105], 0, v[0:1]
	global_load_dwordx4 v[36:39], v[0:1], off nt
.LBB0_397:
	s_or_b64 exec, exec, s[20:21]
	v_add_u32_e32 v92, -3, v100
	v_cmp_lt_u32_e32 vcc, v92, v136
	v_mov_b32_e32 v33, 0
	v_mov_b32_e32 v34, 0
	v_mov_b32_e32 v35, 0
	s_and_saveexec_b64 s[20:21], vcc
	s_cbranch_execz .LBB0_399
	v_lshlrev_b64 v[0:1], 12, v[92:93]
	v_lshl_add_u64 v[0:1], v[104:105], 0, v[0:1]
	global_load_dwordx4 v[32:35], v[0:1], off nt
.LBB0_399:
	s_or_b64 exec, exec, s[20:21]
	v_add_u32_e32 v92, -2, v100
	v_cmp_lt_u32_e32 vcc, v92, v136
	v_mov_b32_e32 v40, 0
	v_mov_b32_e32 v44, 0
	v_mov_b32_e32 v45, 0
	v_mov_b32_e32 v46, 0
	v_mov_b32_e32 v47, 0
	s_and_saveexec_b64 s[20:21], vcc
	s_cbranch_execz .LBB0_401
	v_lshlrev_b64 v[0:1], 12, v[92:93]
	v_lshl_add_u64 v[0:1], v[104:105], 0, v[0:1]
	global_load_dwordx4 v[44:47], v[0:1], off nt
.LBB0_401:
	s_or_b64 exec, exec, s[20:21]
	v_add_u32_e32 v92, -1, v100
	v_cmp_lt_u32_e32 vcc, v92, v136
	v_mov_b32_e32 v41, 0
	v_mov_b32_e32 v42, 0
	v_mov_b32_e32 v43, 0
	s_and_saveexec_b64 s[20:21], vcc
	s_cbranch_execz .LBB0_403
	v_lshlrev_b64 v[0:1], 12, v[92:93]
	v_lshl_add_u64 v[0:1], v[104:105], 0, v[0:1]
	global_load_dwordx4 v[40:43], v[0:1], off nt
.LBB0_403:
	s_or_b64 exec, exec, s[20:21]
	v_cmp_lt_u32_e32 vcc, v100, v136
	v_mov_b32_e32 v52, 0
	v_mov_b32_e32 v60, 0
	v_mov_b32_e32 v61, 0
	v_mov_b32_e32 v62, 0
	v_mov_b32_e32 v63, 0
	s_and_saveexec_b64 s[20:21], vcc
	s_cbranch_execz .LBB0_405
	v_mov_b32_e32 v101, v93
	v_lshlrev_b64 v[0:1], 12, v[100:101]
	v_lshl_add_u64 v[0:1], v[104:105], 0, v[0:1]
	global_load_dwordx4 v[60:63], v[0:1], off nt
.LBB0_405:
	s_or_b64 exec, exec, s[20:21]
	v_or_b32_e32 v116, 1, v100
	v_cmp_lt_u32_e32 vcc, v116, v136
	v_mov_b32_e32 v53, 0
	v_mov_b32_e32 v54, 0
	v_mov_b32_e32 v55, 0
	s_and_saveexec_b64 s[20:21], vcc
	s_cbranch_execz .LBB0_407
	v_mov_b32_e32 v117, v93
	v_lshlrev_b64 v[0:1], 12, v[116:117]
	v_lshl_add_u64 v[0:1], v[104:105], 0, v[0:1]
	global_load_dwordx4 v[52:55], v[0:1], off nt
.LBB0_407:
	s_or_b64 exec, exec, s[20:21]
	v_or_b32_e32 v114, 2, v100
	v_cmp_lt_u32_e32 vcc, v114, v136
	v_mov_b32_e32 v64, 0
	v_mov_b32_e32 v68, 0
	v_mov_b32_e32 v69, 0
	v_mov_b32_e32 v70, 0
	v_mov_b32_e32 v71, 0
	s_and_saveexec_b64 s[20:21], vcc
	s_cbranch_execz .LBB0_409
	v_mov_b32_e32 v115, v93
	v_lshlrev_b64 v[0:1], 12, v[114:115]
	v_lshl_add_u64 v[0:1], v[104:105], 0, v[0:1]
	global_load_dwordx4 v[68:71], v[0:1], off nt
; template <int WIN> __device__ __forceinline__ void pool_chunk(const bf16_t* Ub, bf16_t* Pb, int t0, int L) {
;     constexpr int LEFT = WIN / 2, RIGHT = WIN - 1 - LEFT, NR = 8 + WIN - 1;
;     u32x4 rw[NR];
; #pragma unroll
;     for (int k = 0; k < NR; ++k) { const int t = t0 - LEFT + k; rw[k] = (t >= 0 && t < L) ? *(const u32x4*)(Ub + (size_t)t * DM) : (u32x4){0u, 0u, 0u, 0u}; }
.LBB0_409:
	s_or_b64 exec, exec, s[20:21]
	v_or_b32_e32 v112, 3, v100
	v_cmp_lt_u32_e32 vcc, v112, v136
	v_mov_b32_e32 v65, 0
	v_mov_b32_e32 v66, 0
	v_mov_b32_e32 v67, 0
	s_and_saveexec_b64 s[20:21], vcc
	s_cbranch_execz .LBB0_411
	v_mov_b32_e32 v113, v93
	v_lshlrev_b64 v[0:1], 12, v[112:113]
	v_lshl_add_u64 v[0:1], v[104:105], 0, v[0:1]
	global_load_dwordx4 v[64:67], v[0:1], off nt
.LBB0_411:
	s_or_b64 exec, exec, s[20:21]
	v_or_b32_e32 v110, 4, v100
	v_cmp_lt_u32_e32 vcc, v110, v136
	v_mov_b32_e32 v72, 0
	v_mov_b32_e32 v80, 0
	v_mov_b32_e32 v81, 0
	v_mov_b32_e32 v82, 0
	v_mov_b32_e32 v83, 0
	s_and_saveexec_b64 s[20:21], vcc
	s_cbranch_execz .LBB0_413
	v_mov_b32_e32 v111, v93
	v_lshlrev_b64 v[0:1], 12, v[110:111]
	v_lshl_add_u64 v[0:1], v[104:105], 0, v[0:1]
	global_load_dwordx4 v[80:83], v[0:1], off nt
.LBB0_413:
	s_or_b64 exec, exec, s[20:21]
	v_or_b32_e32 v108, 5, v100
	v_cmp_lt_u32_e32 vcc, v108, v136
	v_mov_b32_e32 v73, 0
	v_mov_b32_e32 v74, 0
	v_mov_b32_e32 v75, 0
	s_and_saveexec_b64 s[20:21], vcc
	s_cbranch_execz .LBB0_415
	v_mov_b32_e32 v109, v93
	v_lshlrev_b64 v[0:1], 12, v[108:109]
	v_lshl_add_u64 v[0:1], v[104:105], 0, v[0:1]
	global_load_dwordx4 v[72:75], v[0:1], off nt
.LBB0_415:
	s_or_b64 exec, exec, s[20:21]
	v_or_b32_e32 v106, 6, v100
	v_cmp_lt_u32_e32 vcc, v106, v136
	v_mov_b32_e32 v84, 0
	v_mov_b32_e32 v88, 0
	v_mov_b32_e32 v89, 0
	v_mov_b32_e32 v90, 0
	v_mov_b32_e32 v91, 0
	s_and_saveexec_b64 s[20:21], vcc
	s_cbranch_execz .LBB0_417
	v_mov_b32_e32 v107, v93
	v_lshlrev_b64 v[0:1], 12, v[106:107]
	v_lshl_add_u64 v[0:1], v[104:105], 0, v[0:1]
	global_load_dwordx4 v[88:91], v[0:1], off nt
.LBB0_417:
	s_or_b64 exec, exec, s[20:21]
	v_or_b32_e32 v102, 7, v100
	v_cmp_lt_u32_e32 vcc, v102, v136
	v_mov_b32_e32 v85, 0
	v_mov_b32_e32 v86, 0
	v_mov_b32_e32 v87, 0
	s_and_saveexec_b64 s[20:21], vcc
	s_cbranch_execz .LBB0_419
	v_mov_b32_e32 v103, v93
	v_lshlrev_b64 v[0:1], 12, v[102:103]
	v_lshl_add_u64 v[0:1], v[104:105], 0, v[0:1]
	global_load_dwordx4 v[84:87], v[0:1], off nt
.LBB0_419:
	s_or_b64 exec, exec, s[20:21]
	v_add_u32_e32 v92, 8, v100
	v_cmp_lt_u32_e32 vcc, v92, v136
	v_mov_b32_e32 v56, 0
	v_mov_b32_e32 v76, 0
	v_mov_b32_e32 v77, 0
	v_mov_b32_e32 v78, 0
	v_mov_b32_e32 v79, 0
	s_and_saveexec_b64 s[20:21], vcc
	s_cbranch_execz .LBB0_421
	v_lshlrev_b64 v[0:1], 12, v[92:93]
	v_lshl_add_u64 v[0:1], v[104:105], 0, v[0:1]
	global_load_dwordx4 v[76:79], v[0:1], off nt
.LBB0_421:
	s_or_b64 exec, exec, s[20:21]
	v_add_u32_e32 v128, 9, v100
	v_cmp_lt_u32_e32 vcc, v128, v136
	v_mov_b32_e32 v57, 0
	v_mov_b32_e32 v58, 0
	v_mov_b32_e32 v59, 0
	s_and_saveexec_b64 s[20:21], vcc
	s_cbranch_execz .LBB0_423
	v_mov_b32_e32 v129, v93
	v_lshlrev_b64 v[0:1], 12, v[128:129]
	v_lshl_add_u64 v[0:1], v[104:105], 0, v[0:1]
	global_load_dwordx4 v[56:59], v[0:1], off nt
.LBB0_423:
	s_or_b64 exec, exec, s[20:21]
	v_add_u32_e32 v126, 10, v100
	v_cmp_lt_u32_e32 vcc, v126, v136
	v_mov_b32_e32 v28, 0
	v_mov_b32_e32 v48, 0
	v_mov_b32_e32 v49, 0
	v_mov_b32_e32 v50, 0
	v_mov_b32_e32 v51, 0
	s_and_saveexec_b64 s[20:21], vcc
	s_cbranch_execz .LBB0_425
	v_mov_b32_e32 v127, v93
	v_lshlrev_b64 v[0:1], 12, v[126:127]
	v_lshl_add_u64 v[0:1], v[104:105], 0, v[0:1]
	global_load_dwordx4 v[48:51], v[0:1], off nt
.LBB0_425:
	s_or_b64 exec, exec, s[20:21]
	v_add_u32_e32 v124, 11, v100
	v_cmp_lt_u32_e32 vcc, v124, v136
	v_mov_b32_e32 v29, 0
	v_mov_b32_e32 v30, 0
	v_mov_b32_e32 v31, 0
	s_and_saveexec_b64 s[20:21], vcc
	s_cbranch_execz .LBB0_427
	v_mov_b32_e32 v125, v93
	v_lshlrev_b64 v[0:1], 12, v[124:125]
	v_lshl_add_u64 v[0:1], v[104:105], 0, v[0:1]
	global_load_dwordx4 v[28:31], v[0:1], off nt
.LBB0_427:
	s_or_b64 exec, exec, s[20:21]
	v_add_u32_e32 v122, 12, v100
	v_cmp_lt_u32_e32 vcc, v122, v136
	v_mov_b32_e32 v4, 0
	v_mov_b32_e32 v20, 0
	v_mov_b32_e32 v21, 0
	v_mov_b32_e32 v22, 0
	v_mov_b32_e32 v23, 0
	s_and_saveexec_b64 s[20:21], vcc
	s_cbranch_execz .LBB0_429
	v_mov_b32_e32 v123, v93
	v_lshlrev_b64 v[0:1], 12, v[122:123]
	v_lshl_add_u64 v[0:1], v[104:105], 0, v[0:1]
	global_load_dwordx4 v[20:23], v[0:1], off nt
.LBB0_429:
	s_or_b64 exec, exec, s[20:21]
	v_add_u32_e32 v120, 13, v100
	v_cmp_lt_u32_e32 vcc, v120, v136
	v_mov_b32_e32 v5, 0
	v_mov_b32_e32 v6, 0
	v_mov_b32_e32 v7, 0
	s_and_saveexec_b64 s[20:21], vcc
	s_cbranch_execz .LBB0_431
	v_mov_b32_e32 v121, v93
	v_lshlrev_b64 v[0:1], 12, v[120:121]
	v_lshl_add_u64 v[0:1], v[104:105], 0, v[0:1]
	global_load_dwordx4 v[4:7], v[0:1], off nt
.LBB0_431:
	s_or_b64 exec, exec, s[20:21]
	v_add_u32_e32 v118, 14, v100
	v_cmp_lt_u32_e32 vcc, v118, v136
	v_mov_b32_e32 v0, 0
	v_mov_b32_e32 v1, 0
	v_mov_b32_e32 v2, 0
	v_mov_b32_e32 v3, 0
	s_and_saveexec_b64 s[20:21], vcc
	s_cbranch_execz .LBB0_433
	v_mov_b32_e32 v119, v93
	v_lshlrev_b64 v[0:1], 12, v[118:119]
	v_lshl_add_u64 v[0:1], v[104:105], 0, v[0:1]
	global_load_dwordx4 v[0:3], v[0:1], off nt

; template <int WIN> __device__ __forceinline__ void pool_chunk(const bf16_t* Ub, bf16_t* Pb, int t0, int L) {
;     constexpr int LEFT = WIN / 2, RIGHT = WIN - 1 - LEFT, NR = 8 + WIN - 1;
;     u32x4 rw[NR];
; #pragma unroll
;     for (int k = 0; k < NR; ++k) { const int t = t0 - LEFT + k; rw[k] = (t >= 0 && t < L) ? *(const u32x4*)(Ub + (size_t)t * DM) : (u32x4){0u, 0u, 0u, 0u}; }
.LBB0_434:
	s_andn2_saveexec_b64 s[18:19], s[18:19]
	s_cbranch_execz .LBB0_466
	v_add_u32_e32 v92, -4, v100
	v_cmp_lt_u32_e32 vcc, v92, v136
	v_mov_b32_e32 v20, 0
	v_mov_b32_e32 v28, 0
	v_mov_b32_e32 v29, 0
	v_mov_b32_e32 v30, 0
	v_mov_b32_e32 v31, 0
	s_and_saveexec_b64 s[20:21], vcc
	s_cbranch_execz .LBB0_437
	v_lshlrev_b64 v[0:1], 12, v[92:93]
	v_lshl_add_u64 v[0:1], v[104:105], 0, v[0:1]
	global_load_dwordx4 v[28:31], v[0:1], off nt
.LBB0_437:
	s_or_b64 exec, exec, s[20:21]
	v_add_u32_e32 v92, -3, v100
	v_cmp_lt_u32_e32 vcc, v92, v136
	v_mov_b32_e32 v21, 0
	v_mov_b32_e32 v22, 0
	v_mov_b32_e32 v23, 0
	s_and_saveexec_b64 s[20:21], vcc
	s_cbranch_execz .LBB0_439
	v_lshlrev_b64 v[0:1], 12, v[92:93]
	v_lshl_add_u64 v[0:1], v[104:105], 0, v[0:1]
	global_load_dwordx4 v[20:23], v[0:1], off nt
.LBB0_439:
	s_or_b64 exec, exec, s[20:21]
	v_add_u32_e32 v92, -2, v100
	v_cmp_lt_u32_e32 vcc, v92, v136
	v_mov_b32_e32 v32, 0
	v_mov_b32_e32 v36, 0
	v_mov_b32_e32 v37, 0
	v_mov_b32_e32 v38, 0
	v_mov_b32_e32 v39, 0
	s_and_saveexec_b64 s[20:21], vcc
	s_cbranch_execz .LBB0_441
	v_lshlrev_b64 v[0:1], 12, v[92:93]
	v_lshl_add_u64 v[0:1], v[104:105], 0, v[0:1]
	global_load_dwordx4 v[36:39], v[0:1], off nt
.LBB0_441:
	s_or_b64 exec, exec, s[20:21]
	v_add_u32_e32 v92, -1, v100
	v_cmp_lt_u32_e32 vcc, v92, v136
	v_mov_b32_e32 v33, 0
	v_mov_b32_e32 v34, 0
	v_mov_b32_e32 v35, 0
	s_and_saveexec_b64 s[20:21], vcc
	s_cbranch_execz .LBB0_443
	v_lshlrev_b64 v[0:1], 12, v[92:93]
	v_lshl_add_u64 v[0:1], v[104:105], 0, v[0:1]
	global_load_dwordx4 v[32:35], v[0:1], off nt
.LBB0_443:
	s_or_b64 exec, exec, s[20:21]
	v_cmp_lt_u32_e32 vcc, v100, v136
	v_mov_b32_e32 v40, 0
	v_mov_b32_e32 v48, 0
	v_mov_b32_e32 v49, 0
	v_mov_b32_e32 v50, 0
	v_mov_b32_e32 v51, 0
	s_and_saveexec_b64 s[20:21], vcc
	s_cbranch_execz .LBB0_445
	v_mov_b32_e32 v101, v93
	v_lshlrev_b64 v[0:1], 12, v[100:101]
	v_lshl_add_u64 v[0:1], v[104:105], 0, v[0:1]
	global_load_dwordx4 v[48:51], v[0:1], off nt
.LBB0_445:
	s_or_b64 exec, exec, s[20:21]
	v_or_b32_e32 v72, 1, v100
	v_cmp_lt_u32_e32 vcc, v72, v136
	v_mov_b32_e32 v41, 0
	v_mov_b32_e32 v42, 0
	v_mov_b32_e32 v43, 0
	s_and_saveexec_b64 s[20:21], vcc
	s_cbranch_execz .LBB0_447
	v_mov_b32_e32 v73, v93
	v_lshlrev_b64 v[0:1], 12, v[72:73]
	v_lshl_add_u64 v[0:1], v[104:105], 0, v[0:1]
	global_load_dwordx4 v[40:43], v[0:1], off nt
.LBB0_447:
	s_or_b64 exec, exec, s[20:21]
	v_or_b32_e32 v68, 2, v100
	v_cmp_lt_u32_e32 vcc, v68, v136
	v_mov_b32_e32 v52, 0
	v_mov_b32_e32 v56, 0
	v_mov_b32_e32 v57, 0
	v_mov_b32_e32 v58, 0
	v_mov_b32_e32 v59, 0
	s_and_saveexec_b64 s[20:21], vcc
	s_cbranch_execz .LBB0_449
	v_mov_b32_e32 v69, v93
	v_lshlrev_b64 v[0:1], 12, v[68:69]
	v_lshl_add_u64 v[0:1], v[104:105], 0, v[0:1]
	global_load_dwordx4 v[56:59], v[0:1], off nt
.LBB0_449:
	s_or_b64 exec, exec, s[20:21]
	v_or_b32_e32 v66, 3, v100
	v_cmp_lt_u32_e32 vcc, v66, v136
	v_mov_b32_e32 v53, 0
	v_mov_b32_e32 v54, 0
	v_mov_b32_e32 v55, 0
	s_and_saveexec_b64 s[20:21], vcc
	s_cbranch_execz .LBB0_451
	v_mov_b32_e32 v67, v93
	v_lshlrev_b64 v[0:1], 12, v[66:67]
	v_lshl_add_u64 v[0:1], v[104:105], 0, v[0:1]
	global_load_dwordx4 v[52:55], v[0:1], off nt
.LBB0_451:
	s_or_b64 exec, exec, s[20:21]
	v_or_b32_e32 v64, 4, v100
	v_cmp_lt_u32_e32 vcc, v64, v136
	v_mov_b32_e32 v24, 0
	v_mov_b32_e32 v44, 0
	v_mov_b32_e32 v45, 0
	v_mov_b32_e32 v46, 0
	v_mov_b32_e32 v47, 0
	s_and_saveexec_b64 s[20:21], vcc
	s_cbranch_execz .LBB0_453
	v_mov_b32_e32 v65, v93
	v_lshlrev_b64 v[0:1], 12, v[64:65]
	v_lshl_add_u64 v[0:1], v[104:105], 0, v[0:1]
	global_load_dwordx4 v[44:47], v[0:1], off nt
.LBB0_453:
	s_or_b64 exec, exec, s[20:21]
	v_or_b32_e32 v62, 5, v100
	v_cmp_lt_u32_e32 vcc, v62, v136
	v_mov_b32_e32 v25, 0
	v_mov_b32_e32 v26, 0
	v_mov_b32_e32 v27, 0
	s_and_saveexec_b64 s[20:21], vcc
	s_cbranch_execz .LBB0_455
	v_mov_b32_e32 v63, v93
	v_lshlrev_b64 v[0:1], 12, v[62:63]
	v_lshl_add_u64 v[0:1], v[104:105], 0, v[0:1]
	global_load_dwordx4 v[24:27], v[0:1], off nt
.LBB0_455:
	s_or_b64 exec, exec, s[20:21]
	v_or_b32_e32 v60, 6, v100
	v_cmp_lt_u32_e32 vcc, v60, v136
	v_mov_b32_e32 v12, 0
	v_mov_b32_e32 v16, 0
	v_mov_b32_e32 v17, 0
	v_mov_b32_e32 v18, 0
	v_mov_b32_e32 v19, 0
	s_and_saveexec_b64 s[20:21], vcc
	s_cbranch_execz .LBB0_457
	v_mov_b32_e32 v61, v93
	v_lshlrev_b64 v[0:1], 12, v[60:61]
	v_lshl_add_u64 v[0:1], v[104:105], 0, v[0:1]
	global_load_dwordx4 v[16:19], v[0:1], off nt
.LBB0_457:
	s_or_b64 exec, exec, s[20:21]
	v_or_b32_e32 v102, 7, v100
	v_cmp_lt_u32_e32 vcc, v102, v136
	v_mov_b32_e32 v13, 0
	v_mov_b32_e32 v14, 0
	v_mov_b32_e32 v15, 0
	s_and_saveexec_b64 s[20:21], vcc
	s_cbranch_execz .LBB0_459
	v_mov_b32_e32 v103, v93
	v_lshlrev_b64 v[0:1], 12, v[102:103]
	v_lshl_add_u64 v[0:1], v[104:105], 0, v[0:1]
	global_load_dwordx4 v[12:15], v[0:1], off nt
.LBB0_459:
	s_or_b64 exec, exec, s[20:21]
	v_add_u32_e32 v92, 8, v100
	v_cmp_lt_u32_e32 vcc, v92, v136
	v_mov_b32_e32 v4, 0
	v_mov_b32_e32 v8, 0
	v_mov_b32_e32 v9, 0
	v_mov_b32_e32 v10, 0
	v_mov_b32_e32 v11, 0
	s_and_saveexec_b64 s[20:21], vcc
	s_cbranch_execz .LBB0_461
	v_lshlrev_b64 v[0:1], 12, v[92:93]
	v_lshl_add_u64 v[0:1], v[104:105], 0, v[0:1]
	global_load_dwordx4 v[8:11], v[0:1], off nt
.LBB0_461:
	s_or_b64 exec, exec, s[20:21]
	v_add_u32_e32 v74, 9, v100
	v_cmp_lt_u32_e32 vcc, v74, v136
	v_mov_b32_e32 v5, 0
	v_mov_b32_e32 v6, 0
	v_mov_b32_e32 v7, 0
	s_and_saveexec_b64 s[20:21], vcc
	s_cbranch_execz .LBB0_463
	v_mov_b32_e32 v75, v93
	v_lshlrev_b64 v[0:1], 12, v[74:75]
	v_lshl_add_u64 v[0:1], v[104:105], 0, v[0:1]
	global_load_dwordx4 v[4:7], v[0:1], off nt
.LBB0_463:
	s_or_b64 exec, exec, s[20:21]
	v_add_u32_e32 v70, 10, v100
	v_cmp_lt_u32_e32 vcc, v70, v136
	v_mov_b32_e32 v0, 0
	v_mov_b32_e32 v1, 0
	v_mov_b32_e32 v2, 0
	v_mov_b32_e32 v3, 0
	s_and_saveexec_b64 s[20:21], vcc
	s_cbranch_execz .LBB0_465
	v_mov_b32_e32 v71, v93
	v_lshlrev_b64 v[0:1], 12, v[70:71]
	v_lshl_add_u64 v[0:1], v[104:105], 0, v[0:1]
	global_load_dwordx4 v[0:3], v[0:1], off nt

; template <int WIN> __device__ __forceinline__ void pool_chunk(const bf16_t* Ub, bf16_t* Pb, int t0, int L) {
;     constexpr int LEFT = WIN / 2, RIGHT = WIN - 1 - LEFT, NR = 8 + WIN - 1;
;     u32x4 rw[NR];
; #pragma unroll
;     for (int k = 0; k < NR; ++k) { const int t = t0 - LEFT + k; rw[k] = (t >= 0 && t < L) ? *(const u32x4*)(Ub + (size_t)t * DM) : (u32x4){0u, 0u, 0u, 0u}; }
.LBB0_467:
	s_andn2_saveexec_b64 s[10:11], s[10:11]
	s_cbranch_execz .LBB0_384
	v_cmp_ne_u32_e32 vcc, 1, v131
	v_add_u32_e32 v92, -1, v100
	s_and_saveexec_b64 s[18:19], vcc
	s_xor_b64 s[18:19], exec, s[18:19]
	s_cbranch_execz .LBB0_488
	v_cmp_lt_u32_e32 vcc, v92, v136
	v_mov_b32_e32 v24, 0
	v_mov_b32_e32 v32, 0
	v_mov_b32_e32 v33, 0
	v_mov_b32_e32 v34, 0
	v_mov_b32_e32 v35, 0
	s_and_saveexec_b64 s[20:21], vcc
	s_cbranch_execz .LBB0_471
	v_lshlrev_b64 v[0:1], 12, v[92:93]
	v_lshl_add_u64 v[0:1], v[104:105], 0, v[0:1]
	global_load_dwordx4 v[32:35], v[0:1], off nt
.LBB0_471:
	s_or_b64 exec, exec, s[20:21]
	v_cmp_lt_u32_e32 vcc, v100, v136
	v_mov_b32_e32 v25, 0
	v_mov_b32_e32 v26, 0
	v_mov_b32_e32 v27, 0
	s_and_saveexec_b64 s[20:21], vcc
	s_cbranch_execz .LBB0_473
	v_mov_b32_e32 v101, v93
	v_lshlrev_b64 v[0:1], 12, v[100:101]
	v_lshl_add_u64 v[0:1], v[104:105], 0, v[0:1]
	global_load_dwordx4 v[24:27], v[0:1], off nt
.LBB0_473:
	s_or_b64 exec, exec, s[20:21]
	v_or_b32_e32 v46, 1, v100
	v_cmp_lt_u32_e32 vcc, v46, v136
	v_mov_b32_e32 v20, 0
	v_mov_b32_e32 v28, 0
	v_mov_b32_e32 v29, 0
	v_mov_b32_e32 v30, 0
	v_mov_b32_e32 v31, 0
	s_and_saveexec_b64 s[20:21], vcc
	s_cbranch_execz .LBB0_475
	v_mov_b32_e32 v47, v93
	v_lshlrev_b64 v[0:1], 12, v[46:47]
	v_lshl_add_u64 v[0:1], v[104:105], 0, v[0:1]
	global_load_dwordx4 v[28:31], v[0:1], off nt
.LBB0_475:
	s_or_b64 exec, exec, s[20:21]
	v_or_b32_e32 v44, 2, v100
	v_cmp_lt_u32_e32 vcc, v44, v136
	v_mov_b32_e32 v21, 0
	v_mov_b32_e32 v22, 0
	v_mov_b32_e32 v23, 0
	s_and_saveexec_b64 s[20:21], vcc
	s_cbranch_execz .LBB0_477
	v_mov_b32_e32 v45, v93
	v_lshlrev_b64 v[0:1], 12, v[44:45]
	v_lshl_add_u64 v[0:1], v[104:105], 0, v[0:1]
	global_load_dwordx4 v[20:23], v[0:1], off nt
.LBB0_477:
	s_or_b64 exec, exec, s[20:21]
	v_or_b32_e32 v42, 3, v100
	v_cmp_lt_u32_e32 vcc, v42, v136
	v_mov_b32_e32 v12, 0
	v_mov_b32_e32 v16, 0
	v_mov_b32_e32 v17, 0
	v_mov_b32_e32 v18, 0
	v_mov_b32_e32 v19, 0
	s_and_saveexec_b64 s[20:21], vcc
	s_cbranch_execz .LBB0_479
	v_mov_b32_e32 v43, v93
	v_lshlrev_b64 v[0:1], 12, v[42:43]
	v_lshl_add_u64 v[0:1], v[104:105], 0, v[0:1]
	global_load_dwordx4 v[16:19], v[0:1], off nt
.LBB0_479:
	s_or_b64 exec, exec, s[20:21]
	v_or_b32_e32 v40, 4, v100
	v_cmp_lt_u32_e32 vcc, v40, v136
	v_mov_b32_e32 v13, 0
	v_mov_b32_e32 v14, 0
	v_mov_b32_e32 v15, 0
	s_and_saveexec_b64 s[20:21], vcc
	s_cbranch_execz .LBB0_481
	v_mov_b32_e32 v41, v93
	v_lshlrev_b64 v[0:1], 12, v[40:41]
	v_lshl_add_u64 v[0:1], v[104:105], 0, v[0:1]
	global_load_dwordx4 v[12:15], v[0:1], off nt
.LBB0_481:
	s_or_b64 exec, exec, s[20:21]
	v_or_b32_e32 v38, 5, v100
	v_cmp_lt_u32_e32 vcc, v38, v136
	v_mov_b32_e32 v4, 0
	v_mov_b32_e32 v8, 0
	v_mov_b32_e32 v9, 0
	v_mov_b32_e32 v10, 0
	v_mov_b32_e32 v11, 0
	s_and_saveexec_b64 s[20:21], vcc
	s_cbranch_execz .LBB0_483
	v_mov_b32_e32 v39, v93
	v_lshlrev_b64 v[0:1], 12, v[38:39]
	v_lshl_add_u64 v[0:1], v[104:105], 0, v[0:1]
	global_load_dwordx4 v[8:11], v[0:1], off nt
.LBB0_483:
	s_or_b64 exec, exec, s[20:21]
	v_or_b32_e32 v36, 6, v100
	v_cmp_lt_u32_e32 vcc, v36, v136
	v_mov_b32_e32 v5, 0
	v_mov_b32_e32 v6, 0
	v_mov_b32_e32 v7, 0
	s_and_saveexec_b64 s[20:21], vcc
	s_cbranch_execz .LBB0_485
	v_mov_b32_e32 v37, v93
	v_lshlrev_b64 v[0:1], 12, v[36:37]
	v_lshl_add_u64 v[0:1], v[104:105], 0, v[0:1]
	global_load_dwordx4 v[4:7], v[0:1], off nt
.LBB0_485:
	s_or_b64 exec, exec, s[20:21]
	v_or_b32_e32 v102, 7, v100
	v_cmp_lt_u32_e32 vcc, v102, v136
	v_mov_b32_e32 v0, 0
	v_mov_b32_e32 v1, 0
	v_mov_b32_e32 v2, 0
	v_mov_b32_e32 v3, 0
	s_and_saveexec_b64 s[20:21], vcc
	s_cbranch_execz .LBB0_487
	v_mov_b32_e32 v103, v93
	v_lshlrev_b64 v[0:1], 12, v[102:103]
	v_lshl_add_u64 v[0:1], v[104:105], 0, v[0:1]
	global_load_dwordx4 v[0:3], v[0:1], off nt

; template <int WIN> __device__ __forceinline__ void pool_chunk(const bf16_t* Ub, bf16_t* Pb, int t0, int L) {
;     constexpr int LEFT = WIN / 2, RIGHT = WIN - 1 - LEFT, NR = 8 + WIN - 1;
;     u32x4 rw[NR];
; #pragma unroll
;     for (int k = 0; k < NR; ++k) { const int t = t0 - LEFT + k; rw[k] = (t >= 0 && t < L) ? *(const u32x4*)(Ub + (size_t)t * DM) : (u32x4){0u, 0u, 0u, 0u}; }
.LBB0_488:
	s_andn2_saveexec_b64 s[18:19], s[18:19]
	s_cbranch_execz .LBB0_383
	v_add_u32_e32 v0, -2, v100
	v_cmp_lt_u32_e32 vcc, v0, v136
	v_mov_b32_e32 v24, 0
	v_mov_b32_e32 v32, 0
	v_mov_b32_e32 v33, 0
	v_mov_b32_e32 v34, 0
	v_mov_b32_e32 v35, 0
	s_and_saveexec_b64 s[20:21], vcc
	s_cbranch_execz .LBB0_491
	v_mov_b32_e32 v1, v93
	v_lshlrev_b64 v[0:1], 12, v[0:1]
	v_lshl_add_u64 v[0:1], v[104:105], 0, v[0:1]
	global_load_dwordx4 v[32:35], v[0:1], off nt
.LBB0_491:
	s_or_b64 exec, exec, s[20:21]
	v_cmp_lt_u32_e32 vcc, v92, v136
	v_mov_b32_e32 v25, 0
	v_mov_b32_e32 v26, 0
	v_mov_b32_e32 v27, 0
	s_and_saveexec_b64 s[20:21], vcc
	s_cbranch_execz .LBB0_493
	v_lshlrev_b64 v[0:1], 12, v[92:93]
	v_lshl_add_u64 v[0:1], v[104:105], 0, v[0:1]
	global_load_dwordx4 v[24:27], v[0:1], off nt
.LBB0_493:
	s_or_b64 exec, exec, s[20:21]
	v_cmp_lt_u32_e32 vcc, v100, v136
	v_mov_b32_e32 v36, 0
	v_mov_b32_e32 v40, 0
	v_mov_b32_e32 v41, 0
	v_mov_b32_e32 v42, 0
	v_mov_b32_e32 v43, 0
	s_and_saveexec_b64 s[20:21], vcc
	s_cbranch_execz .LBB0_495
	v_mov_b32_e32 v101, v93
	v_lshlrev_b64 v[0:1], 12, v[100:101]
	v_lshl_add_u64 v[0:1], v[104:105], 0, v[0:1]
	global_load_dwordx4 v[40:43], v[0:1], off nt
.LBB0_495:
	s_or_b64 exec, exec, s[20:21]
	v_or_b32_e32 v54, 1, v100
	v_cmp_lt_u32_e32 vcc, v54, v136
	v_mov_b32_e32 v37, 0
	v_mov_b32_e32 v38, 0
	v_mov_b32_e32 v39, 0
	s_and_saveexec_b64 s[20:21], vcc
	s_cbranch_execz .LBB0_497
	v_mov_b32_e32 v55, v93
	v_lshlrev_b64 v[0:1], 12, v[54:55]
	v_lshl_add_u64 v[0:1], v[104:105], 0, v[0:1]
	global_load_dwordx4 v[36:39], v[0:1], off nt
.LBB0_497:
	s_or_b64 exec, exec, s[20:21]
	v_or_b32_e32 v52, 2, v100
	v_cmp_lt_u32_e32 vcc, v52, v136
	v_mov_b32_e32 v20, 0
	v_mov_b32_e32 v28, 0
	v_mov_b32_e32 v29, 0
	v_mov_b32_e32 v30, 0
	v_mov_b32_e32 v31, 0
	s_and_saveexec_b64 s[20:21], vcc
	s_cbranch_execz .LBB0_499
	v_mov_b32_e32 v53, v93
	v_lshlrev_b64 v[0:1], 12, v[52:53]
	v_lshl_add_u64 v[0:1], v[104:105], 0, v[0:1]
	global_load_dwordx4 v[28:31], v[0:1], off nt
.LBB0_499:
	s_or_b64 exec, exec, s[20:21]
	v_or_b32_e32 v50, 3, v100
	v_cmp_lt_u32_e32 vcc, v50, v136
	v_mov_b32_e32 v21, 0
	v_mov_b32_e32 v22, 0
	v_mov_b32_e32 v23, 0
	s_and_saveexec_b64 s[20:21], vcc
	s_cbranch_execz .LBB0_501
	v_mov_b32_e32 v51, v93
	v_lshlrev_b64 v[0:1], 12, v[50:51]
	v_lshl_add_u64 v[0:1], v[104:105], 0, v[0:1]
	global_load_dwordx4 v[20:23], v[0:1], off nt
.LBB0_501:
	s_or_b64 exec, exec, s[20:21]
	v_or_b32_e32 v48, 4, v100
	v_cmp_lt_u32_e32 vcc, v48, v136
	v_mov_b32_e32 v12, 0
	v_mov_b32_e32 v16, 0
	v_mov_b32_e32 v17, 0
	v_mov_b32_e32 v18, 0
	v_mov_b32_e32 v19, 0
	s_and_saveexec_b64 s[20:21], vcc
	s_cbranch_execz .LBB0_503
	v_mov_b32_e32 v49, v93
	v_lshlrev_b64 v[0:1], 12, v[48:49]
	v_lshl_add_u64 v[0:1], v[104:105], 0, v[0:1]
	global_load_dwordx4 v[16:19], v[0:1], off nt
.LBB0_503:
	s_or_b64 exec, exec, s[20:21]
	v_or_b32_e32 v46, 5, v100
	v_cmp_lt_u32_e32 vcc, v46, v136
	v_mov_b32_e32 v13, 0
	v_mov_b32_e32 v14, 0
	v_mov_b32_e32 v15, 0
	s_and_saveexec_b64 s[20:21], vcc
	s_cbranch_execz .LBB0_505
	v_mov_b32_e32 v47, v93
	v_lshlrev_b64 v[0:1], 12, v[46:47]
	v_lshl_add_u64 v[0:1], v[104:105], 0, v[0:1]
	global_load_dwordx4 v[12:15], v[0:1], off nt
.LBB0_505:
	s_or_b64 exec, exec, s[20:21]
	v_or_b32_e32 v44, 6, v100
	v_cmp_lt_u32_e32 vcc, v44, v136
	v_mov_b32_e32 v4, 0
	v_mov_b32_e32 v8, 0
	v_mov_b32_e32 v9, 0
	v_mov_b32_e32 v10, 0
	v_mov_b32_e32 v11, 0
	s_and_saveexec_b64 s[20:21], vcc
	s_cbranch_execz .LBB0_507
	v_mov_b32_e32 v45, v93
	v_lshlrev_b64 v[0:1], 12, v[44:45]
	v_lshl_add_u64 v[0:1], v[104:105], 0, v[0:1]
	global_load_dwordx4 v[8:11], v[0:1], off nt
.LBB0_507:
	s_or_b64 exec, exec, s[20:21]
	v_or_b32_e32 v102, 7, v100
	v_cmp_lt_u32_e32 vcc, v102, v136
	v_mov_b32_e32 v5, 0
	v_mov_b32_e32 v6, 0
	v_mov_b32_e32 v7, 0
	s_and_saveexec_b64 s[20:21], vcc
	s_cbranch_execz .LBB0_509
	v_mov_b32_e32 v103, v93
	v_lshlrev_b64 v[0:1], 12, v[102:103]
	v_lshl_add_u64 v[0:1], v[104:105], 0, v[0:1]
	global_load_dwordx4 v[4:7], v[0:1], off nt
.LBB0_509:
	s_or_b64 exec, exec, s[20:21]
	v_add_u32_e32 v92, 8, v100
	v_cmp_lt_u32_e32 vcc, v92, v136
	v_mov_b32_e32 v0, 0
	v_mov_b32_e32 v1, 0
	v_mov_b32_e32 v2, 0
	v_mov_b32_e32 v3, 0
	s_and_saveexec_b64 s[20:21], vcc
	s_cbranch_execz .LBB0_382
	v_lshlrev_b64 v[0:1], 12, v[92:93]
	v_lshl_add_u64 v[0:1], v[104:105], 0, v[0:1]
	global_load_dwordx4 v[0:3], v[0:1], off nt
	s_branch .LBB0_382
